# lever 2 prologue de-serialisation: the phase-3 weight-conversion items (and the copy run inside the barrier-5 wait) issue their four 16-row slab loads together and consume them behind counted vmcnt wa
# baseline (speedup 1.0000x reference)
.LBB0_390:
	s_and_b64 vcc, exec, s[4:5]
	s_cbranch_vccz .LBB0_392
	s_lshl_b32 s0, s77, 6
	s_and_b32 s4, s0, 0x3c0
	s_lshl_b32 s0, s77, 2
	s_and_b32 s0, s0, 0x1fc0
	s_add_i32 s36, s0, 0xffffec00
	v_mov_b32_e32 v10, v207
	s_lshl_b64 s[0:1], s[36:37], 2
	v_ashrrev_i32_e32 v8, 4, v10
	v_readlane_b32 s5, v255, 7
	s_add_u32 s0, s5, s0
	v_readlane_b32 s5, v255, 8
	v_lshlrev_b32_e32 v0, 4, v10
	v_add_u32_e32 v6, s4, v8
	s_addc_u32 s1, s5, s1
	v_and_b32_e32 v204, 0xf0, v0
	v_ashrrev_i32_e32 v7, 31, v6
	v_lshl_add_u64 v[4:5], s[0:1], 0, v[204:205]
	v_lshlrev_b64 v[0:1], 12, v[6:7]
	v_lshl_add_u64 v[0:1], v[4:5], 0, v[0:1]
	global_load_dwordx4 v[40:43], v[0:1], off nt
	v_add_u32_e32 v58, 16, v6
	v_ashrrev_i32_e32 v59, 31, v58
	v_lshlrev_b64 v[58:59], 12, v[58:59]
	v_lshl_add_u64 v[58:59], v[4:5], 0, v[58:59]
	global_load_dwordx4 v[44:47], v[58:59], off nt
	v_add_u32_e32 v60, 32, v6
	v_ashrrev_i32_e32 v61, 31, v60
	v_lshlrev_b64 v[60:61], 12, v[60:61]
	v_lshl_add_u64 v[60:61], v[4:5], 0, v[60:61]
	global_load_dwordx4 v[48:51], v[60:61], off nt
	v_add_u32_e32 v62, 48, v6
	v_ashrrev_i32_e32 v63, 31, v62
	v_lshlrev_b64 v[62:63], 12, v[62:63]
	v_lshl_add_u64 v[62:63], v[4:5], 0, v[62:63]
	global_load_dwordx4 v[52:55], v[62:63], off nt
	v_mad_u64_u32 v[8:9], s[0:1], v8, s90, v[204:205]
	v_add_u32_e32 v7, 0x1040, v8
	v_ashrrev_i32_e32 v22, 3, v10
	s_lshl_b32 s0, s4, 1
	v_readlane_b32 s1, v255, 9
	s_add_u32 s0, s1, s0
	v_readlane_b32 s1, v255, 10
	s_addc_u32 s1, s1, 0
	s_waitcnt vmcnt(3)
	ds_write2_b32 v8, v40, v41 offset1:1
	ds_write2_b32 v8, v42, v43 offset0:2 offset1:3
	s_waitcnt vmcnt(2)
	ds_write2_b32 v7, v44, v45 offset1:1
	v_add_u32_e32 v0, 0x1048, v8
	ds_write2_b32 v0, v46, v47 offset1:1
	v_add_u32_e32 v7, 0x2080, v8
	s_waitcnt vmcnt(1)
	ds_write2_b32 v7, v48, v49 offset1:1
	v_add_u32_e32 v0, 0x2088, v8
	ds_write2_b32 v0, v50, v51 offset1:1
	v_add_u32_e32 v4, 0x30c0, v8
	s_waitcnt vmcnt(0)
	ds_write2_b32 v4, v52, v53 offset1:1
	v_add_u32_e32 v0, 0x30c8, v8
	ds_write2_b32 v0, v54, v55 offset1:1
	v_lshlrev_b32_e32 v0, 3, v10
	v_and_b32_e32 v0, 56, v0
	v_lshlrev_b32_e32 v204, 1, v0
	v_mul_u32_u24_e32 v0, 0x104, v0
	v_lshl_add_u32 v0, v22, 2, v0
	s_waitcnt lgkmcnt(0)
	s_barrier
	ds_read2_b32 v[6:7], v0 offset1:32
	ds_read2_b32 v[8:9], v0 offset0:65 offset1:97
	ds_read2_b32 v[10:11], v0 offset0:130 offset1:162
	ds_read2_b32 v[12:13], v0 offset0:195 offset1:227
	v_add_u32_e32 v0, 0x400, v0
	ds_read2_b32 v[14:15], v0 offset0:4 offset1:36
	ds_read2_b32 v[16:17], v0 offset0:69 offset1:101
	ds_read2_b32 v[18:19], v0 offset0:134 offset1:166
	ds_read2_b32 v[20:21], v0 offset0:199 offset1:231
	v_add_u32_e32 v22, s36, v22
	v_ashrrev_i32_e32 v23, 31, v22
	v_lshl_add_u64 v[4:5], s[0:1], 0, v[204:205]
	v_lshlrev_b64 v[24:25], 11, v[22:23]
	s_waitcnt lgkmcnt(6)
	v_cvt_pk_bf16_f32 v0, v6, v8
	s_waitcnt lgkmcnt(4)
	v_cvt_pk_bf16_f32 v1, v10, v12
	s_waitcnt lgkmcnt(2)
	v_cvt_pk_bf16_f32 v2, v14, v16
	s_waitcnt lgkmcnt(0)
	v_cvt_pk_bf16_f32 v3, v18, v20
	v_lshl_add_u64 v[24:25], v[4:5], 0, v[24:25]
	v_add_u32_e32 v6, 32, v22
	global_store_dwordx4 v[24:25], v[0:3], off
	s_nop 1
	v_cvt_pk_bf16_f32 v0, v7, v9
	v_ashrrev_i32_e32 v7, 31, v6
	v_lshlrev_b64 v[6:7], 11, v[6:7]
	v_cvt_pk_bf16_f32 v1, v11, v13
	v_cvt_pk_bf16_f32 v2, v15, v17
	v_cvt_pk_bf16_f32 v3, v19, v21
	v_lshl_add_u64 v[4:5], v[4:5], 0, v[6:7]
	global_store_dwordx4 v[4:5], v[0:3], off
	s_barrier

.LBB0_393:
	s_andn2_b64 vcc, exec, s[4:5]
	s_cbranch_vccnz .LBB0_395
	s_lshl_b32 s0, s77, 6
	s_and_b32 s4, s0, 0x3c0
	s_lshl_b32 s0, s77, 2
	s_and_b32 s0, s0, 0x1fc0
	s_add_i32 s36, s0, 0xfffff000
	v_mov_b32_e32 v10, v207
	s_lshl_b64 s[0:1], s[36:37], 2
	v_ashrrev_i32_e32 v8, 4, v10
	s_add_u32 s0, s72, s0
	v_lshlrev_b32_e32 v0, 4, v10
	v_add_u32_e32 v6, s4, v8
	s_addc_u32 s1, s73, s1
	v_and_b32_e32 v204, 0xf0, v0
	v_ashrrev_i32_e32 v7, 31, v6
	v_lshl_add_u64 v[4:5], s[0:1], 0, v[204:205]
	v_lshlrev_b64 v[0:1], 12, v[6:7]
	v_lshl_add_u64 v[0:1], v[4:5], 0, v[0:1]
	global_load_dwordx4 v[40:43], v[0:1], off nt
	v_add_u32_e32 v58, 16, v6
	v_ashrrev_i32_e32 v59, 31, v58
	v_lshlrev_b64 v[58:59], 12, v[58:59]
	v_lshl_add_u64 v[58:59], v[4:5], 0, v[58:59]
	global_load_dwordx4 v[44:47], v[58:59], off nt
	v_add_u32_e32 v60, 32, v6
	v_ashrrev_i32_e32 v61, 31, v60
	v_lshlrev_b64 v[60:61], 12, v[60:61]
	v_lshl_add_u64 v[60:61], v[4:5], 0, v[60:61]
	global_load_dwordx4 v[48:51], v[60:61], off nt
	v_add_u32_e32 v62, 48, v6
	v_ashrrev_i32_e32 v63, 31, v62
	v_lshlrev_b64 v[62:63], 12, v[62:63]
	v_lshl_add_u64 v[62:63], v[4:5], 0, v[62:63]
	global_load_dwordx4 v[52:55], v[62:63], off nt
	v_mad_u64_u32 v[8:9], s[0:1], v8, s90, v[204:205]
	v_add_u32_e32 v7, 0x1040, v8
	v_ashrrev_i32_e32 v22, 3, v10
	s_lshl_b32 s0, s4, 1
	s_add_u32 s0, s80, s0
	s_addc_u32 s1, s81, 0
	s_waitcnt vmcnt(3)
	ds_write2_b32 v8, v40, v41 offset1:1
	ds_write2_b32 v8, v42, v43 offset0:2 offset1:3
	s_waitcnt vmcnt(2)
	ds_write2_b32 v7, v44, v45 offset1:1
	v_add_u32_e32 v0, 0x1048, v8
	ds_write2_b32 v0, v46, v47 offset1:1
	v_add_u32_e32 v7, 0x2080, v8
	s_waitcnt vmcnt(1)
	ds_write2_b32 v7, v48, v49 offset1:1
	v_add_u32_e32 v0, 0x2088, v8
	ds_write2_b32 v0, v50, v51 offset1:1
	v_add_u32_e32 v4, 0x30c0, v8
	s_waitcnt vmcnt(0)
	ds_write2_b32 v4, v52, v53 offset1:1
	v_add_u32_e32 v0, 0x30c8, v8
	ds_write2_b32 v0, v54, v55 offset1:1
	v_lshlrev_b32_e32 v0, 3, v10
	v_and_b32_e32 v0, 56, v0
	v_lshlrev_b32_e32 v204, 1, v0
	v_mul_u32_u24_e32 v0, 0x104, v0
	v_lshl_add_u32 v0, v22, 2, v0
	s_waitcnt lgkmcnt(0)
	s_barrier
	ds_read2_b32 v[6:7], v0 offset1:32
	ds_read2_b32 v[8:9], v0 offset0:65 offset1:97
	ds_read2_b32 v[10:11], v0 offset0:130 offset1:162
	ds_read2_b32 v[12:13], v0 offset0:195 offset1:227
	v_add_u32_e32 v0, 0x400, v0
	ds_read2_b32 v[14:15], v0 offset0:4 offset1:36
	ds_read2_b32 v[16:17], v0 offset0:69 offset1:101
	ds_read2_b32 v[18:19], v0 offset0:134 offset1:166
	ds_read2_b32 v[20:21], v0 offset0:199 offset1:231
	v_add_u32_e32 v22, s36, v22
	v_ashrrev_i32_e32 v23, 31, v22
	v_lshl_add_u64 v[4:5], s[0:1], 0, v[204:205]
	v_lshlrev_b64 v[24:25], 11, v[22:23]
	s_waitcnt lgkmcnt(6)
	v_cvt_pk_bf16_f32 v0, v6, v8
	s_waitcnt lgkmcnt(4)
	v_cvt_pk_bf16_f32 v1, v10, v12
	s_waitcnt lgkmcnt(2)
	v_cvt_pk_bf16_f32 v2, v14, v16
	s_waitcnt lgkmcnt(0)
	v_cvt_pk_bf16_f32 v3, v18, v20
	v_lshl_add_u64 v[24:25], v[4:5], 0, v[24:25]
	v_add_u32_e32 v6, 32, v22
	global_store_dwordx4 v[24:25], v[0:3], off
	s_nop 1
	v_cvt_pk_bf16_f32 v0, v7, v9
	v_ashrrev_i32_e32 v7, 31, v6
	v_lshlrev_b64 v[6:7], 11, v[6:7]
	v_cvt_pk_bf16_f32 v1, v11, v13
	v_cvt_pk_bf16_f32 v2, v15, v17
	v_cvt_pk_bf16_f32 v3, v19, v21
	v_lshl_add_u64 v[4:5], v[4:5], 0, v[6:7]
	global_store_dwordx4 v[4:5], v[0:3], off
	s_barrier

.LBB0_396:
	s_andn2_b64 vcc, exec, s[4:5]
	s_cbranch_vccnz .LBB0_398
	s_lshl_b32 s0, s77, 6
	s_and_b32 s4, s0, 0x3c0
	s_lshl_b32 s0, s77, 2
	s_and_b32 s0, s0, 0xfc0
	s_add_i32 s36, s0, 0xfffffc00
	v_mov_b32_e32 v8, v207
	s_lshl_b64 s[0:1], s[36:37], 2
	s_add_u32 s0, s70, s0
	v_lshlrev_b32_e32 v0, 4, v8
	v_ashrrev_i32_e32 v6, 4, v8
	s_addc_u32 s1, s71, s1
	v_and_b32_e32 v204, 0xf0, v0
	v_lshl_add_u64 v[4:5], s[0:1], 0, v[204:205]
	v_add_u32_e32 v9, s4, v6
	v_mad_i64_i32 v[0:1], s[0:1], v9, s91, v[4:5]
	global_load_dwordx4 v[40:43], v[0:1], off nt
	v_add_u32_e32 v58, 16, v9
	v_mad_i64_i32 v[58:59], s[0:1], v58, s91, v[4:5]
	global_load_dwordx4 v[44:47], v[58:59], off nt
	v_add_u32_e32 v60, 32, v9
	v_mad_i64_i32 v[60:61], s[0:1], v60, s91, v[4:5]
	global_load_dwordx4 v[48:51], v[60:61], off nt
	v_add_u32_e32 v62, 48, v9
	v_mad_i64_i32 v[62:63], s[0:1], v62, s91, v[4:5]
	global_load_dwordx4 v[52:55], v[62:63], off nt
	v_mad_u64_u32 v[6:7], s[0:1], v6, s90, v[204:205]
	v_add_u32_e32 v7, 0x1040, v6
	v_ashrrev_i32_e32 v22, 3, v8
	s_waitcnt vmcnt(3)
	ds_write2_b32 v6, v40, v41 offset1:1
	ds_write2_b32 v6, v42, v43 offset0:2 offset1:3
	s_waitcnt vmcnt(2)
	ds_write2_b32 v7, v44, v45 offset1:1
	v_add_u32_e32 v0, 0x1048, v6
	ds_write2_b32 v0, v46, v47 offset1:1
	v_add_u32_e32 v7, 0x2080, v6
	s_waitcnt vmcnt(1)
	ds_write2_b32 v7, v48, v49 offset1:1
	v_add_u32_e32 v0, 0x2088, v6
	ds_write2_b32 v0, v50, v51 offset1:1
	v_add_u32_e32 v4, 0x30c0, v6
	s_lshl_b32 s0, s4, 1
	s_add_u32 s0, s58, s0
	s_addc_u32 s1, s59, 0
	s_waitcnt vmcnt(0)
	ds_write2_b32 v4, v52, v53 offset1:1
	v_add_u32_e32 v0, 0x30c8, v6
	ds_write2_b32 v0, v54, v55 offset1:1
	v_lshlrev_b32_e32 v0, 3, v8
	v_and_b32_e32 v0, 56, v0
	v_lshlrev_b32_e32 v204, 1, v0
	v_mul_u32_u24_e32 v0, 0x104, v0
	v_lshl_add_u32 v0, v22, 2, v0
	s_waitcnt lgkmcnt(0)
	s_barrier
	ds_read2_b32 v[6:7], v0 offset1:32
	ds_read2_b32 v[8:9], v0 offset0:65 offset1:97
	ds_read2_b32 v[10:11], v0 offset0:130 offset1:162
	ds_read2_b32 v[12:13], v0 offset0:195 offset1:227
	v_add_u32_e32 v0, 0x400, v0
	ds_read2_b32 v[14:15], v0 offset0:4 offset1:36
	ds_read2_b32 v[16:17], v0 offset0:69 offset1:101
	ds_read2_b32 v[18:19], v0 offset0:134 offset1:166
	ds_read2_b32 v[20:21], v0 offset0:199 offset1:231
	v_add_u32_e32 v22, s36, v22
	v_ashrrev_i32_e32 v23, 31, v22
	v_lshl_add_u64 v[4:5], s[0:1], 0, v[204:205]
	v_lshlrev_b64 v[24:25], 11, v[22:23]
	s_waitcnt lgkmcnt(6)
	v_cvt_pk_bf16_f32 v0, v6, v8
	s_waitcnt lgkmcnt(4)
	v_cvt_pk_bf16_f32 v1, v10, v12
	s_waitcnt lgkmcnt(2)
	v_cvt_pk_bf16_f32 v2, v14, v16
	s_waitcnt lgkmcnt(0)
	v_cvt_pk_bf16_f32 v3, v18, v20
	v_lshl_add_u64 v[24:25], v[4:5], 0, v[24:25]
	v_add_u32_e32 v6, 32, v22
	global_store_dwordx4 v[24:25], v[0:3], off
	s_nop 1
	v_cvt_pk_bf16_f32 v0, v7, v9
	v_ashrrev_i32_e32 v7, 31, v6
	v_lshlrev_b64 v[6:7], 11, v[6:7]
	v_cvt_pk_bf16_f32 v1, v11, v13
	v_cvt_pk_bf16_f32 v2, v15, v17
	v_cvt_pk_bf16_f32 v3, v19, v21
	v_lshl_add_u64 v[4:5], v[4:5], 0, v[6:7]
	global_store_dwordx4 v[4:5], v[0:3], off
	s_barrier

.Lcv_loop:
	s_lshl_b32 s0, s7, 6
	s_and_b32 s6, s0, 0x3c0
	s_lshl_b32 s0, s7, 2
	s_and_b32 s0, s0, 0xfc0
	s_add_i32 s36, s0, 0xfffffc00
	v_mov_b32_e32 v8, v207
	s_lshl_b64 s[0:1], s[36:37], 2
	s_add_u32 s0, s8, s0
	v_lshlrev_b32_e32 v0, 4, v8
	v_ashrrev_i32_e32 v6, 4, v8
	s_addc_u32 s1, s9, s1
	v_and_b32_e32 v204, 0xf0, v0
	v_lshl_add_u64 v[4:5], s[0:1], 0, v[204:205]
	v_add_u32_e32 v9, s6, v6
	v_mad_i64_i32 v[0:1], s[0:1], v9, s10, v[4:5]
	global_load_dwordx4 v[40:43], v[0:1], off nt
	v_add_u32_e32 v58, 16, v9
	v_mad_i64_i32 v[58:59], s[0:1], v58, s10, v[4:5]
	global_load_dwordx4 v[44:47], v[58:59], off nt
	v_add_u32_e32 v60, 32, v9
	v_mad_i64_i32 v[60:61], s[0:1], v60, s10, v[4:5]
	global_load_dwordx4 v[48:51], v[60:61], off nt
	v_add_u32_e32 v62, 48, v9
	v_mad_i64_i32 v[62:63], s[0:1], v62, s10, v[4:5]
	global_load_dwordx4 v[52:55], v[62:63], off nt
	v_mad_u64_u32 v[6:7], s[0:1], v6, s11, v[204:205]
	v_add_u32_e32 v7, 0x1040, v6
	v_ashrrev_i32_e32 v22, 3, v8
	s_waitcnt vmcnt(3)
	ds_write2_b32 v6, v40, v41 offset1:1
	ds_write2_b32 v6, v42, v43 offset0:2 offset1:3
	s_waitcnt vmcnt(2)
	ds_write2_b32 v7, v44, v45 offset1:1
	v_add_u32_e32 v0, 0x1048, v6
	ds_write2_b32 v0, v46, v47 offset1:1
	v_add_u32_e32 v7, 0x2080, v6
	s_waitcnt vmcnt(1)
	ds_write2_b32 v7, v48, v49 offset1:1
	v_add_u32_e32 v0, 0x2088, v6
	ds_write2_b32 v0, v50, v51 offset1:1
	v_add_u32_e32 v4, 0x30c0, v6
	s_lshl_b32 s0, s6, 1
	s_add_u32 s0, s58, s0
	s_addc_u32 s1, s59, 0
	s_waitcnt vmcnt(0)
	ds_write2_b32 v4, v52, v53 offset1:1
	v_add_u32_e32 v0, 0x30c8, v6
	ds_write2_b32 v0, v54, v55 offset1:1
	v_lshlrev_b32_e32 v0, 3, v8
	v_and_b32_e32 v0, 56, v0
	v_lshlrev_b32_e32 v204, 1, v0
	v_mul_u32_u24_e32 v0, 0x104, v0
	v_lshl_add_u32 v0, v22, 2, v0
	s_waitcnt lgkmcnt(0)
	s_barrier
	ds_read2_b32 v[6:7], v0 offset1:32
	ds_read2_b32 v[8:9], v0 offset0:65 offset1:97
	ds_read2_b32 v[10:11], v0 offset0:130 offset1:162
	ds_read2_b32 v[12:13], v0 offset0:195 offset1:227
	v_add_u32_e32 v0, 0x400, v0
	ds_read2_b32 v[14:15], v0 offset0:4 offset1:36
	ds_read2_b32 v[16:17], v0 offset0:69 offset1:101
	ds_read2_b32 v[18:19], v0 offset0:134 offset1:166
	ds_read2_b32 v[20:21], v0 offset0:199 offset1:231
	v_add_u32_e32 v22, s36, v22
	v_ashrrev_i32_e32 v23, 31, v22
	v_lshl_add_u64 v[4:5], s[0:1], 0, v[204:205]
	v_lshlrev_b64 v[24:25], 11, v[22:23]
	s_waitcnt lgkmcnt(6)
	v_cvt_pk_bf16_f32 v0, v6, v8
	s_waitcnt lgkmcnt(4)
	v_cvt_pk_bf16_f32 v1, v10, v12
	s_waitcnt lgkmcnt(2)
	v_cvt_pk_bf16_f32 v2, v14, v16
	s_waitcnt lgkmcnt(0)
	v_cvt_pk_bf16_f32 v3, v18, v20
	v_lshl_add_u64 v[24:25], v[4:5], 0, v[24:25]
	v_add_u32_e32 v6, 32, v22
	global_store_dwordx4 v[24:25], v[0:3], off
	s_nop 1
	v_cvt_pk_bf16_f32 v0, v7, v9
	v_ashrrev_i32_e32 v7, 31, v6
	v_lshlrev_b64 v[6:7], 11, v[6:7]
	v_cvt_pk_bf16_f32 v1, v11, v13
	v_cvt_pk_bf16_f32 v2, v15, v17
	v_cvt_pk_bf16_f32 v3, v19, v21
	v_lshl_add_u64 v[4:5], v[4:5], 0, v[6:7]
	global_store_dwordx4 v[4:5], v[0:3], off
	s_barrier
	s_addk_i32 s7, 0x200
	s_cmpk_lt_i32 s7, 0x400
	s_cbranch_scc1 .Lcv_loop
	s_waitcnt vmcnt(0)
	s_barrier
	s_mov_b64 s[12:13], exec
	v_readlane_b32 s0, v255, 1
	v_readlane_b32 s1, v255, 2
	s_nop 1
	s_mov_b64 exec, s[0:1]
	s_cbranch_execz .Lthr0_b5
	v_readlane_b32 s98, v255, 5
	v_readlane_b32 s99, v255, 6
	v_mov_b32_e32 v19, 0x10000
	ds_read_b32 v2, v19
	s_lshl_b32 s0, s3, 3
	s_add_i32 s0, s0, 0x380
	v_mov_b32_e32 v3, s0
	v_mov_b32_e32 v4, 1
	s_nop 2
	global_atomic_add v3, v3, v4, s[98:99] sc0
	s_waitcnt vmcnt(0) lgkmcnt(0)
	v_add_u32_e32 v3, 1, v3
	v_cmp_eq_u32_e32 vcc, v3, v2
	s_cbranch_vccz .Lcv_sig_done
	buffer_wbl2 sc1
	s_waitcnt vmcnt(0)
	v_mov_b32_e32 v3, 0x3c0
	global_atomic_add v3, v4, s[98:99]
